# grid barrier: L1 invalidate (buffer_inv sc1) only at the three layer-boundary barriers; buffer lifetime audit shows no buffer is read, rewritten by another CU and re-read within one layer
# speedup vs baseline: 1.0330x; 1.0330x over previous
.LBB0_1457:
	s_mov_b32 s2, 0x11080
	s_bitcmp1_b32 s2, s50
	s_cbranch_scc0 .Lxb_noinv
	buffer_inv sc1
	s_waitcnt vmcnt(0)
